# nt hint additionally on cache-phase f32 inputs, O-side row reads and the second raw source
# baseline (speedup 1.0000x reference)
.LBB0_217:
	s_mov_b64 s[20:21], -1
	s_and_b64 vcc, exec, s[0:1]
	s_cbranch_vccz .LBB0_223
	s_mov_b64 s[22:23], -1
	v_mov_b32_e32 v0, 8
	v_mov_b64_e32 v[30:31], 18
	v_mov_b64_e32 v[24:25], 9
	v_mov_b64_e32 v[28:29], 0x42c00000
	v_mov_b64_e32 v[32:33], s[14:15]
	v_mov_b64_e32 v[26:27], v[8:9]
	s_and_saveexec_b64 s[20:21], s[6:7]
	v_mov_b32_e32 v0, 6
	v_mov_b64_e32 v[30:31], 16
	v_mov_b64_e32 v[24:25], 7
	v_mov_b64_e32 v[28:29], 0x43200000
	v_mov_b64_e32 v[32:33], s[12:13]
	s_orn2_b64 s[22:23], s[8:9], exec
	v_mov_b64_e32 v[26:27], v[2:3]
	s_or_b64 exec, exec, s[20:21]
	s_and_saveexec_b64 s[20:21], s[22:23]
	s_cbranch_execz .LBB0_222
	global_load_dwordx2 v[32:33], v[32:33], off
	s_ashr_i32 s22, s16, 8
	s_lshl_b32 s18, s22, 1
	v_readlane_b32 s24, v254, 54
	s_add_i32 s18, s18, s24
	s_and_b32 s23, s16, 0xff
	s_ashr_i32 s19, s18, 31
	v_lshlrev_b32_e64 v0, v0, s23
	v_lshlrev_b64 v[30:31], v30, s[18:19]
	v_lshlrev_b32_e32 v0, 2, v0
	s_mulk_i32 s22, 0x500
	s_or_b32 s18, s22, s23
	s_addk_i32 s18, 0x2000
	s_ashr_i32 s19, s18, 31
	v_lshl_add_u64 v[28:29], s[2:3], 0, v[28:29]
	v_lshlrev_b64 v[24:25], v24, s[18:19]
	v_lshl_add_u64 v[24:25], v[28:29], 0, v[24:25]
	v_lshl_add_u64 v[24:25], v[26:27], 1, v[24:25]
	v_readlane_b32 s25, v254, 55
	s_waitcnt vmcnt(0)
	v_lshl_add_u64 v[30:31], v[32:33], 0, v[30:31]
	v_lshl_add_u64 v[30:31], v[30:31], 0, v[0:1]
	v_lshl_add_u64 v[34:35], v[26:27], 2, v[30:31]
	global_load_dwordx4 v[30:33], v[34:35], off nt
	s_nop 0
	global_load_dwordx4 v[34:37], v[34:35], off offset:16 nt
	s_waitcnt vmcnt(1)
	v_cvt_pk_bf16_f32 v28, v30, v31
	v_cvt_pk_bf16_f32 v29, v32, v33
	s_waitcnt vmcnt(0)
	v_cvt_pk_bf16_f32 v30, v34, v35
	v_cvt_pk_bf16_f32 v31, v36, v37
	global_store_dwordx4 v[24:25], v[28:31], off

.LBB0_224:
	s_ashr_i32 s19, s16, 8
	s_load_dwordx8 s[20:27], s[10:11], 0x10
	s_lshl_b32 s28, s19, 1
	v_readlane_b32 s30, v254, 54
	v_readlane_b32 s31, v254, 55
	s_add_i32 s30, s28, s30
	s_ashr_i32 s31, s30, 31
	s_lshl_b64 s[36:37], s[30:31], 3
	s_and_b32 s18, s16, 0xff
	v_mov_b32_e32 v23, v1
	v_mov_b32_e32 v27, s37
	v_or_b32_e32 v26, s36, v6
	v_or_b32_e32 v7, s18, v5
	s_waitcnt lgkmcnt(0)
	v_lshl_add_u64 v[34:35], s[20:21], 0, v[22:23]
	v_lshlrev_b64 v[36:37], 17, v[26:27]
	v_lshlrev_b32_e32 v38, 8, v7
	v_mov_b32_e32 v39, v1
	v_lshl_add_u64 v[26:27], v[34:35], 0, v[36:37]
	v_lshl_add_u64 v[30:31], v[26:27], 0, v[38:39]
	global_load_dwordx4 v[26:29], v[30:31], off offset:16 nt
	s_nop 0
	global_load_dwordx4 v[30:33], v[30:31], off nt
	s_mulk_i32 s19, 0x500
	s_or_b32 s20, s19, s18
	s_ashr_i32 s21, s20, 31
	s_lshl_b32 s19, s18, 9
	s_add_u32 s22, s22, s19
	s_addc_u32 s23, s23, 0
	v_lshlrev_b32_e32 v0, 2, v4
	v_lshl_add_u64 v[24:25], s[22:23], 0, v[0:1]
	s_lshl_b64 s[22:23], s[20:21], 11
	v_lshl_add_u64 v[40:41], v[18:19], 0, s[22:23]
	s_waitcnt vmcnt(0)
	v_cvt_pk_bf16_f32 v30, v30, v31
	v_cvt_pk_bf16_f32 v31, v32, v33
	v_cvt_pk_bf16_f32 v32, v26, v27
	v_cvt_pk_bf16_f32 v33, v28, v29
	global_store_dwordx4 v[40:41], v[30:33], off
	s_nop 1
	v_lshl_add_u64 v[30:31], v[24:25], 0, v[36:37]
	global_load_dwordx4 v[26:29], v[30:31], off offset:16 nt
	s_nop 0
	global_load_dwordx4 v[30:33], v[30:31], off nt
	v_lshl_add_u64 v[36:37], v[20:21], 0, s[22:23]
	s_waitcnt vmcnt(0)
	v_cvt_pk_bf16_f32 v30, v30, v31
	v_cvt_pk_bf16_f32 v31, v32, v33
	v_cvt_pk_bf16_f32 v32, v26, v27
	v_mov_b32_e32 v27, s37
	v_or_b32_e32 v26, s36, v10
	v_lshlrev_b64 v[42:43], 17, v[26:27]
	v_cvt_pk_bf16_f32 v33, v28, v29
	v_lshl_add_u64 v[26:27], v[34:35], 0, v[42:43]
	global_store_dwordx4 v[36:37], v[30:33], off
	s_nop 1
	v_lshl_add_u64 v[30:31], v[26:27], 0, v[38:39]
	global_load_dwordx4 v[26:29], v[30:31], off offset:16 nt
	s_nop 0
	global_load_dwordx4 v[30:33], v[30:31], off nt
	s_waitcnt vmcnt(0)
	v_cvt_pk_bf16_f32 v30, v30, v31
	v_cvt_pk_bf16_f32 v31, v32, v33
	v_cvt_pk_bf16_f32 v32, v26, v27
	v_cvt_pk_bf16_f32 v33, v28, v29
	global_store_dwordx4 v[40:41], v[30:33], off offset:1024
	v_lshl_add_u64 v[28:29], v[24:25], 0, v[42:43]
	global_load_dwordx4 v[24:27], v[28:29], off offset:16 nt
	s_nop 0
	global_load_dwordx4 v[28:31], v[28:29], off nt
	s_waitcnt vmcnt(0)
	v_cvt_pk_bf16_f32 v28, v28, v29
	v_cvt_pk_bf16_f32 v29, v30, v31
	v_cvt_pk_bf16_f32 v30, v24, v25
	v_cvt_pk_bf16_f32 v31, v26, v27
	global_store_dwordx4 v[36:37], v[28:31], off offset:1024
	s_and_saveexec_b64 s[22:23], s[4:5]
	s_cbranch_execz .LBB0_215
	s_lshl_b64 s[28:29], s[30:31], 9
	v_or_b32_e32 v7, s28, v12
	v_mov_b32_e32 v25, s29
	v_or_b32_e32 v24, s18, v7
	v_lshlrev_b64 v[32:33], 9, v[24:25]
	v_lshl_add_u64 v[24:25], s[24:25], 0, v[32:33]
	v_lshl_add_u64 v[28:29], v[24:25], 0, v[0:1]
	global_load_dwordx4 v[24:27], v[28:29], off offset:16 nt
	s_nop 0
	global_load_dwordx4 v[28:31], v[28:29], off nt
	s_lshl_b64 s[18:19], s[20:21], 9
	s_waitcnt vmcnt(0)
	v_cvt_pk_bf16_f32 v28, v28, v29
	v_cvt_pk_bf16_f32 v29, v30, v31
	v_cvt_pk_bf16_f32 v30, v24, v25
	v_cvt_pk_bf16_f32 v31, v26, v27
	v_lshl_add_u64 v[24:25], v[14:15], 0, s[18:19]
	global_store_dwordx4 v[24:25], v[28:31], off
	v_lshl_add_u64 v[24:25], s[26:27], 0, v[32:33]
	s_nop 0
	v_lshl_add_u64 v[28:29], v[24:25], 0, v[0:1]
	global_load_dwordx4 v[24:27], v[28:29], off offset:16 nt
	s_nop 0
	global_load_dwordx4 v[28:31], v[28:29], off nt
	s_waitcnt vmcnt(0)
	v_cvt_pk_bf16_f32 v28, v28, v29
	v_cvt_pk_bf16_f32 v29, v30, v31
	v_cvt_pk_bf16_f32 v30, v24, v25
	v_cvt_pk_bf16_f32 v31, v26, v27
	v_lshl_add_u64 v[24:25], v[16:17], 0, s[18:19]
	global_store_dwordx4 v[24:25], v[28:31], off
	s_branch .LBB0_215

.LBB0_284:
	s_and_b64 vcc, exec, s[14:15]
	s_cbranch_vccz .LBB0_261
	v_lshl_add_u64 v[2:3], s[2:3], 0, v[96:97]
	v_add_co_u32_e32 v4, vcc, 0x28a00000, v2
	v_lshl_add_u64 v[18:19], s[2:3], 0, v[100:101]
	s_nop 0
	v_addc_co_u32_e32 v5, vcc, 0, v3, vcc
	v_add_co_u32_e32 v6, vcc, 0x28c80000, v2
	v_lshl_add_u64 v[20:21], s[2:3], 0, v[102:103]
	s_nop 0
	v_addc_co_u32_e32 v7, vcc, 0, v3, vcc
	global_load_dwordx4 v[14:17], v[4:5], off nt
	global_load_dwordx4 v[10:13], v[6:7], off nt
	v_add_co_u32_e32 v4, vcc, 0x28f00000, v2
	s_nop 1
	v_addc_co_u32_e32 v5, vcc, 0, v3, vcc
	v_add_co_u32_e32 v2, vcc, 0x29180000, v2
	s_nop 1
	v_addc_co_u32_e32 v3, vcc, 0, v3, vcc
	global_load_dwordx4 v[6:9], v[4:5], off nt
	s_nop 0
	global_load_dwordx4 v[2:5], v[2:3], off nt
	s_nop 0
	global_load_dwordx4 v[22:25], v[18:19], off nt
	s_nop 0
	global_load_dwordx4 v[18:21], v[20:21], off nt
	s_and_saveexec_b64 s[14:15], s[4:5]
	s_cbranch_execz .LBB0_289
	v_lshl_add_u64 v[26:27], s[2:3], 0, v[98:99]
	v_add_co_u32_e32 v28, vcc, 0x29180000, v26
	s_mov_b32 s1, 0x28a00000
	s_nop 0
	v_addc_co_u32_e32 v29, vcc, 0, v27, vcc
	global_load_ushort v30, v[28:29], off offset:128
	v_add_co_u32_e32 v28, vcc, 0x28c80000, v26
	s_load_dwordx2 s[26:27], s[20:21], 0xd8
	s_nop 0
	v_addc_co_u32_e32 v29, vcc, 0, v27, vcc
	global_load_ushort v28, v[28:29], off offset:128
	s_waitcnt vmcnt(0)
	v_lshlrev_b32_e32 v29, 16, v28
	v_lshlrev_b32_e32 v28, 16, v30
	v_add_co_u32_e32 v30, vcc, 0x28f00000, v26
	s_nop 1
	v_addc_co_u32_e32 v31, vcc, 0, v27, vcc
	v_add_co_u32_e32 v26, vcc, s1, v26
	global_load_ushort v30, v[30:31], off offset:128
	s_nop 0
	v_addc_co_u32_e32 v27, vcc, 0, v27, vcc
	global_load_ushort v26, v[26:27], off offset:128
	s_waitcnt vmcnt(0)
	v_lshlrev_b32_e32 v27, 16, v26
	v_lshlrev_b32_e32 v26, 16, v30
	v_pk_add_f32 v[26:27], v[28:29], v[26:27]
	s_nop 0
	v_add_f32_e32 v28, v26, v27
	s_waitcnt lgkmcnt(0)
	v_lshl_add_u64 v[26:27], v[76:77], 2, s[26:27]
	global_load_dword v26, v[26:27], off
	s_waitcnt vmcnt(0)
	v_add_f32_e32 v26, v26, v28
	s_and_saveexec_b64 s[26:27], s[6:7]
	s_cbranch_execz .LBB0_288
	s_mov_b32 s1, 0xbfb8aa3b
	v_mul_f32_e64 v27, |v26|, s1
	v_exp_f32_e32 v27, v27
	s_mov_b32 s1, 0x3a83126f
	v_max_f32_e32 v26, v26, v26
	v_min_f32_e32 v26, 0, v26
	v_add_f32_e32 v28, 1.0, v27
	v_log_f32_e32 v28, v28
	v_fma_f32 v29, v27, -0.5, 1.0
	v_mul_f32_e32 v29, v27, v29
	v_cmp_gt_f32_e32 vcc, s1, v27
	v_mul_f32_e32 v28, 0x3f317218, v28
	s_nop 0
	v_cndmask_b32_e32 v27, v28, v29, vcc
	v_sub_f32_e32 v26, v26, v27

.LBB0_463:
	v_add_u32_e32 v56, s2, v70
	v_ashrrev_i32_e32 v57, 31, v56
	v_lshlrev_b64 v[2:3], 11, v[56:57]
	v_lshl_add_u64 v[2:3], s[62:63], 0, v[2:3]
	v_lshl_add_u64 v[2:3], v[2:3], 0, v[0:1]
	global_load_dwordx4 v[34:37], v[2:3], off nt
	v_add_co_u32_e32 v2, vcc, 0x1400000, v2
	v_mov_b64_e32 v[10:11], s[74:75]
	s_nop 0
	v_addc_co_u32_e32 v3, vcc, 0, v3, vcc
	global_load_dwordx4 v[38:41], v[2:3], off nt
	v_mad_i64_i32 v[2:3], s[2:3], v56, s85, v[10:11]
	v_lshl_add_u64 v[2:3], v[2:3], 0, v[0:1]
	v_add_co_u32_e32 v2, vcc, s4, v2
	v_add_u32_e32 v54, 32, v56
	s_nop 0
	v_addc_co_u32_e32 v3, vcc, 0, v3, vcc
	global_load_dwordx4 v[58:61], v[2:3], off offset:2048 nt
	v_ashrrev_i32_e32 v55, 31, v54
	v_lshlrev_b64 v[2:3], 11, v[54:55]
	v_lshl_add_u64 v[2:3], s[62:63], 0, v[2:3]
	v_lshl_add_u64 v[2:3], v[2:3], 0, v[0:1]
	global_load_dwordx4 v[26:29], v[2:3], off nt
	v_add_co_u32_e32 v2, vcc, s5, v2
	v_add_u32_e32 v52, 64, v56
	s_nop 0
	v_addc_co_u32_e32 v3, vcc, 0, v3, vcc
	global_load_dwordx4 v[30:33], v[2:3], off nt
	v_mad_i64_i32 v[2:3], s[2:3], v54, s85, v[10:11]
	v_lshl_add_u64 v[2:3], v[2:3], 0, v[0:1]
	v_add_co_u32_e32 v2, vcc, s4, v2
	v_ashrrev_i32_e32 v53, 31, v52
	s_nop 0
	v_addc_co_u32_e32 v3, vcc, 0, v3, vcc
	global_load_dwordx4 v[42:45], v[2:3], off offset:2048 nt
	v_lshlrev_b64 v[2:3], 11, v[52:53]
	v_lshl_add_u64 v[2:3], s[62:63], 0, v[2:3]
	v_lshl_add_u64 v[2:3], v[2:3], 0, v[0:1]
	global_load_dwordx4 v[14:17], v[2:3], off nt
	v_add_co_u32_e32 v2, vcc, s5, v2
	v_add_u32_e32 v50, 0x60, v56
	s_nop 0
	v_addc_co_u32_e32 v3, vcc, 0, v3, vcc
	global_load_dwordx4 v[18:21], v[2:3], off nt
	v_mad_i64_i32 v[2:3], s[2:3], v52, s85, v[10:11]
	v_lshl_add_u64 v[2:3], v[2:3], 0, v[0:1]
	v_add_co_u32_e32 v2, vcc, s4, v2
	v_ashrrev_i32_e32 v51, 31, v50
	s_nop 0
	v_addc_co_u32_e32 v3, vcc, 0, v3, vcc
	global_load_dwordx4 v[22:25], v[2:3], off offset:2048 nt
	v_lshlrev_b64 v[2:3], 11, v[50:51]
	v_lshl_add_u64 v[2:3], s[62:63], 0, v[2:3]
	v_lshl_add_u64 v[6:7], v[2:3], 0, v[0:1]
	global_load_dwordx4 v[2:5], v[6:7], off nt
	v_add_co_u32_e32 v6, vcc, s5, v6
	v_mad_i64_i32 v[10:11], s[2:3], v50, s85, v[10:11]
	s_nop 0
	v_addc_co_u32_e32 v7, vcc, 0, v7, vcc
	v_lshl_add_u64 v[10:11], v[10:11], 0, v[0:1]
	v_add_co_u32_e32 v10, vcc, s4, v10
	global_load_dwordx4 v[6:9], v[6:7], off nt
	s_nop 0
	v_addc_co_u32_e32 v11, vcc, 0, v11, vcc
	global_load_dwordx4 v[10:13], v[10:11], off offset:2048 nt
	s_movk_i32 s2, 0x80
	s_and_b64 vcc, exec, s[0:1]
	s_mov_b64 s[0:1], 0
	s_waitcnt vmcnt(0)
	v_lshlrev_b32_e32 v72, 16, v36
	v_and_b32_e32 v73, 0xffff0000, v36
	v_lshlrev_b32_e32 v80, 16, v35
	v_and_b32_e32 v81, 0xffff0000, v35
	v_lshlrev_b32_e32 v84, 16, v34
	v_and_b32_e32 v85, 0xffff0000, v34
	v_lshlrev_b32_e32 v36, 16, v40
	v_lshlrev_b32_e32 v34, 16, v38
	v_and_b32_e32 v35, 0xffff0000, v38
	v_lshlrev_b32_e32 v82, 16, v39
	v_and_b32_e32 v83, 0xffff0000, v39
	v_pk_add_f32 v[34:35], v[84:85], v[34:35]
	v_pk_add_f32 v[80:81], v[80:81], v[82:83]
	v_pk_mul_f32 v[38:39], v[34:35], v[34:35]
	v_pk_mul_f32 v[82:83], v[80:81], v[80:81]
	v_lshlrev_b32_e32 v62, 16, v58
	v_and_b32_e32 v63, 0xffff0000, v58
	v_lshlrev_b32_e32 v66, 16, v60
	v_and_b32_e32 v67, 0xffff0000, v60
	v_lshlrev_b32_e32 v64, 16, v59
	v_and_b32_e32 v65, 0xffff0000, v59
	v_mul_f32_e32 v58, 0xbfb8aa3b, v62
	v_mul_f32_e32 v59, 0xbfb8aa3b, v63
	v_mul_f32_e32 v62, 0xbfb8aa3b, v66
	v_mul_f32_e32 v63, 0xbfb8aa3b, v67
	v_lshlrev_b32_e32 v66, 16, v37
	v_and_b32_e32 v67, 0xffff0000, v37
	v_and_b32_e32 v37, 0xffff0000, v40
	v_pk_add_f32 v[36:37], v[72:73], v[36:37]
	global_load_dwordx4 v[72:75], v[48:49], off offset:16
	global_load_dwordx4 v[76:79], v[48:49], off
	v_add_f32_e32 v38, v38, v39
	v_lshlrev_b32_e32 v68, 16, v61
	v_and_b32_e32 v69, 0xffff0000, v61
	v_add_f32_e32 v38, v82, v38
	v_mul_f32_e32 v60, 0xbfb8aa3b, v64
	v_mul_f32_e32 v61, 0xbfb8aa3b, v65
	v_mul_f32_e32 v64, 0xbfb8aa3b, v68
	v_mul_f32_e32 v65, 0xbfb8aa3b, v69
	v_lshlrev_b32_e32 v68, 16, v41
	v_and_b32_e32 v69, 0xffff0000, v41
	v_pk_mul_f32 v[40:41], v[36:37], v[36:37]
	v_add_f32_e32 v38, v83, v38
	v_pk_add_f32 v[66:67], v[66:67], v[68:69]
	v_add_f32_e32 v38, v40, v38
	v_pk_mul_f32 v[68:69], v[66:67], v[66:67]
	v_add_f32_e32 v38, v41, v38
	v_add_f32_e32 v38, v68, v38
	v_add_f32_e32 v38, v69, v38
	v_exp_f32_e32 v62, v62
	v_exp_f32_e32 v63, v63
	v_add_f32_dpp v38, v38, v38 quad_perm:[1,0,3,2] row_mask:0xf bank_mask:0xf bound_ctrl:1
	v_exp_f32_e32 v64, v64
	v_exp_f32_e32 v65, v65
	v_add_f32_dpp v38, v38, v38 quad_perm:[2,3,0,1] row_mask:0xf bank_mask:0xf bound_ctrl:1
	v_exp_f32_e32 v58, v58
	v_exp_f32_e32 v59, v59
	v_add_f32_dpp v38, v38, v38 row_half_mirror row_mask:0xf bank_mask:0xf bound_ctrl:1
	v_exp_f32_e32 v60, v60
	v_exp_f32_e32 v61, v61
	v_add_f32_dpp v38, v38, v38 row_mirror row_mask:0xf bank_mask:0xf bound_ctrl:1
	v_fmamk_f32 v38, v38, 0x3c000000, v233
	v_rsq_f32_e32 v38, v38
	v_add_f32_e32 v62, 1.0, v62
	v_add_f32_e32 v63, 1.0, v63
	v_add_f32_e32 v64, 1.0, v64
	v_add_f32_e32 v65, 1.0, v65
	v_add_f32_e32 v58, 1.0, v58
	v_add_f32_e32 v59, 1.0, v59
	v_add_f32_e32 v60, 1.0, v60
	v_add_f32_e32 v61, 1.0, v61
	v_rcp_f32_e32 v62, v62
	v_rcp_f32_e32 v63, v63
	v_rcp_f32_e32 v64, v64
	v_rcp_f32_e32 v65, v65
	v_rcp_f32_e32 v58, v58
	v_rcp_f32_e32 v59, v59
	v_rcp_f32_e32 v60, v60
	v_rcp_f32_e32 v61, v61
	v_pk_mul_f32 v[34:35], v[34:35], v[38:39] op_sel_hi:[1,0]
	v_pk_mul_f32 v[40:41], v[80:81], v[38:39] op_sel_hi:[1,0]
	v_pk_mul_f32 v[36:37], v[36:37], v[38:39] op_sel_hi:[1,0]
	v_pk_mul_f32 v[38:39], v[66:67], v[38:39] op_sel_hi:[1,0]
	v_lshlrev_b32_e32 v68, 16, v26
	v_and_b32_e32 v69, 0xffff0000, v26
	v_lshlrev_b32_e32 v26, 16, v30
	v_lshlrev_b32_e32 v66, 16, v31
	v_and_b32_e32 v67, 0xffff0000, v31
	s_waitcnt vmcnt(1)
	v_pk_mul_f32 v[36:37], v[72:73], v[36:37]
	v_pk_mul_f32 v[38:39], v[38:39], v[74:75]
	s_waitcnt vmcnt(0)
	v_pk_mul_f32 v[34:35], v[76:77], v[34:35]
	v_pk_mul_f32 v[40:41], v[78:79], v[40:41]
	v_pk_mul_f32 v[36:37], v[62:63], v[36:37]
	v_pk_mul_f32 v[38:39], v[64:65], v[38:39]
	v_pk_mul_f32 v[34:35], v[58:59], v[34:35]
	v_pk_mul_f32 v[40:41], v[60:61], v[40:41]
	v_cvt_pk_bf16_f32 v36, v36, v37
	v_cvt_pk_bf16_f32 v37, v38, v39
	v_lshlrev_b64 v[38:39], 12, v[56:57]
	v_cvt_pk_bf16_f32 v34, v34, v35
	v_cvt_pk_bf16_f32 v35, v40, v41
	v_lshl_add_u64 v[38:39], v[46:47], 0, v[38:39]
	global_store_dwordx4 v[38:39], v[34:37], off
	v_lshlrev_b32_e32 v38, 16, v44
	v_and_b32_e32 v39, 0xffff0000, v44
	v_lshlrev_b32_e32 v34, 16, v42
	v_mul_f32_e32 v34, 0xbfb8aa3b, v34
	v_exp_f32_e32 v34, v34
	v_and_b32_e32 v35, 0xffff0000, v42
	v_lshlrev_b32_e32 v36, 16, v43
	v_and_b32_e32 v37, 0xffff0000, v43
	v_add_f32_e32 v34, 1.0, v34
	v_rcp_f32_e32 v40, v34
	v_mul_f32_e32 v34, 0xbfb8aa3b, v35
	v_exp_f32_e32 v34, v34
	v_lshlrev_b32_e32 v56, 16, v45
	v_and_b32_e32 v57, 0xffff0000, v45
	v_and_b32_e32 v35, 0xffff0000, v29
	v_add_f32_e32 v34, 1.0, v34
	v_rcp_f32_e32 v41, v34
	v_mul_f32_e32 v34, 0xbfb8aa3b, v36
	v_exp_f32_e32 v34, v34
	v_lshlrev_b32_e32 v36, 16, v33
	v_lshlrev_b32_e32 v64, 16, v27
	v_and_b32_e32 v65, 0xffff0000, v27
	v_add_f32_e32 v34, 1.0, v34
	v_rcp_f32_e32 v42, v34
	v_mul_f32_e32 v34, 0xbfb8aa3b, v37
	v_exp_f32_e32 v34, v34
	v_and_b32_e32 v37, 0xffff0000, v33
	v_and_b32_e32 v27, 0xffff0000, v30
	v_pk_add_f32 v[26:27], v[68:69], v[26:27]
	v_add_f32_e32 v34, 1.0, v34
	v_rcp_f32_e32 v43, v34
	v_mul_f32_e32 v34, 0xbfb8aa3b, v38
	v_exp_f32_e32 v34, v34
	v_pk_add_f32 v[64:65], v[64:65], v[66:67]
	v_pk_mul_f32 v[30:31], v[26:27], v[26:27]
	v_pk_mul_f32 v[66:67], v[64:65], v[64:65]
	v_add_f32_e32 v34, 1.0, v34
	v_rcp_f32_e32 v44, v34
	v_mul_f32_e32 v34, 0xbfb8aa3b, v39
	v_exp_f32_e32 v34, v34
	v_add_f32_e32 v30, v30, v31
	v_add_f32_e32 v30, v66, v30
	v_add_f32_e32 v30, v67, v30
	v_add_f32_e32 v34, 1.0, v34
	v_rcp_f32_e32 v45, v34
	v_mul_f32_e32 v34, 0xbfb8aa3b, v56
	v_exp_f32_e32 v34, v34
	s_nop 0
	v_add_f32_e32 v34, 1.0, v34
	v_rcp_f32_e32 v56, v34
	v_mul_f32_e32 v34, 0xbfb8aa3b, v57
	v_exp_f32_e32 v34, v34
	s_nop 0
	v_add_f32_e32 v34, 1.0, v34
	v_rcp_f32_e32 v57, v34
	v_lshlrev_b32_e32 v34, 16, v29
	v_pk_add_f32 v[58:59], v[34:35], v[36:37]
	v_lshlrev_b32_e32 v34, 16, v28
	v_and_b32_e32 v35, 0xffff0000, v28
	v_lshlrev_b32_e32 v28, 16, v32
	v_and_b32_e32 v29, 0xffff0000, v32
	v_pk_add_f32 v[28:29], v[34:35], v[28:29]
	global_load_dwordx4 v[32:35], v[48:49], off offset:16
	global_load_dwordx4 v[36:39], v[48:49], off
	v_pk_mul_f32 v[62:63], v[28:29], v[28:29]
	v_pk_mul_f32 v[60:61], v[58:59], v[58:59]
	v_add_f32_e32 v30, v62, v30
	v_add_f32_e32 v30, v63, v30
	v_add_f32_e32 v30, v60, v30
	v_add_f32_e32 v30, v61, v30
	s_nop 1
	v_add_f32_dpp v30, v30, v30 quad_perm:[1,0,3,2] row_mask:0xf bank_mask:0xf bound_ctrl:1
	s_nop 1
	v_add_f32_dpp v30, v30, v30 quad_perm:[2,3,0,1] row_mask:0xf bank_mask:0xf bound_ctrl:1
	s_nop 1
	v_add_f32_dpp v30, v30, v30 row_half_mirror row_mask:0xf bank_mask:0xf bound_ctrl:1
	s_nop 1
	v_add_f32_dpp v30, v30, v30 row_mirror row_mask:0xf bank_mask:0xf bound_ctrl:1
	v_fmamk_f32 v30, v30, 0x3c000000, v233
	v_rsq_f32_e32 v30, v30
	s_nop 0
	v_pk_mul_f32 v[26:27], v[26:27], v[30:31] op_sel_hi:[1,0]
	v_pk_mul_f32 v[28:29], v[28:29], v[30:31] op_sel_hi:[1,0]
	s_waitcnt vmcnt(0)
	v_pk_mul_f32 v[26:27], v[36:37], v[26:27]
	v_pk_mul_f32 v[36:37], v[64:65], v[30:31] op_sel_hi:[1,0]
	v_pk_mul_f32 v[30:31], v[58:59], v[30:31] op_sel_hi:[1,0]
	v_pk_mul_f32 v[28:29], v[32:33], v[28:29]
	v_pk_mul_f32 v[30:31], v[30:31], v[34:35]
	v_pk_mul_f32 v[36:37], v[38:39], v[36:37]
	v_pk_mul_f32 v[28:29], v[44:45], v[28:29]
	v_pk_mul_f32 v[30:31], v[56:57], v[30:31]
	v_pk_mul_f32 v[26:27], v[40:41], v[26:27]
	v_pk_mul_f32 v[36:37], v[42:43], v[36:37]
	v_cvt_pk_bf16_f32 v28, v28, v29
	v_cvt_pk_bf16_f32 v29, v30, v31
	v_lshlrev_b64 v[30:31], 12, v[54:55]
	v_cvt_pk_bf16_f32 v26, v26, v27
	v_cvt_pk_bf16_f32 v27, v36, v37
	v_lshl_add_u64 v[30:31], v[46:47], 0, v[30:31]
	global_store_dwordx4 v[30:31], v[26:29], off
	v_lshlrev_b32_e32 v32, 16, v24
	v_and_b32_e32 v24, 0xffff0000, v24
	v_lshlrev_b32_e32 v26, 16, v22
	v_and_b32_e32 v22, 0xffff0000, v22
	v_mul_f32_e32 v22, 0xbfb8aa3b, v22
	v_exp_f32_e32 v22, v22
	v_lshlrev_b32_e32 v27, 16, v23
	v_and_b32_e32 v23, 0xffff0000, v23
	v_lshlrev_b32_e32 v34, 16, v25
	v_add_f32_e32 v22, 1.0, v22
	v_rcp_f32_e32 v29, v22
	v_mul_f32_e32 v22, 0xbfb8aa3b, v27
	v_exp_f32_e32 v22, v22
	v_and_b32_e32 v25, 0xffff0000, v25
	v_mul_f32_e32 v26, 0xbfb8aa3b, v26
	v_exp_f32_e32 v26, v26
	v_add_f32_e32 v22, 1.0, v22
	v_rcp_f32_e32 v30, v22
	v_mul_f32_e32 v22, 0xbfb8aa3b, v23
	v_exp_f32_e32 v22, v22
	v_and_b32_e32 v23, 0xffff0000, v17
	v_add_f32_e32 v26, 1.0, v26
	v_rcp_f32_e32 v28, v26
	v_add_f32_e32 v22, 1.0, v22
	v_rcp_f32_e32 v31, v22
	v_mul_f32_e32 v22, 0xbfb8aa3b, v32
	v_exp_f32_e32 v22, v22
	v_lshlrev_b32_e32 v42, 16, v15
	v_and_b32_e32 v43, 0xffff0000, v15
	v_lshlrev_b32_e32 v54, 16, v14
	v_add_f32_e32 v22, 1.0, v22
	v_rcp_f32_e32 v32, v22
	v_mul_f32_e32 v22, 0xbfb8aa3b, v24
	v_exp_f32_e32 v22, v22
	v_lshlrev_b32_e32 v24, 16, v21
	v_and_b32_e32 v55, 0xffff0000, v14
	v_lshlrev_b32_e32 v14, 16, v18
	v_add_f32_e32 v22, 1.0, v22
	v_rcp_f32_e32 v33, v22
	v_mul_f32_e32 v22, 0xbfb8aa3b, v34
	v_exp_f32_e32 v22, v22
	v_and_b32_e32 v15, 0xffff0000, v18
	v_lshlrev_b32_e32 v44, 16, v19
	v_and_b32_e32 v45, 0xffff0000, v19
	v_add_f32_e32 v22, 1.0, v22
	v_rcp_f32_e32 v34, v22
	v_mul_f32_e32 v22, 0xbfb8aa3b, v25
	v_exp_f32_e32 v22, v22
	v_and_b32_e32 v25, 0xffff0000, v21
	v_pk_add_f32 v[14:15], v[54:55], v[14:15]
	v_pk_add_f32 v[42:43], v[42:43], v[44:45]
	v_add_f32_e32 v22, 1.0, v22
	v_rcp_f32_e32 v35, v22
	v_lshlrev_b32_e32 v22, 16, v17
	v_pk_add_f32 v[36:37], v[22:23], v[24:25]
	v_lshlrev_b32_e32 v22, 16, v16
	v_and_b32_e32 v23, 0xffff0000, v16
	v_lshlrev_b32_e32 v16, 16, v20
	v_and_b32_e32 v17, 0xffff0000, v20
	v_pk_add_f32 v[16:17], v[22:23], v[16:17]
	global_load_dwordx4 v[20:23], v[48:49], off offset:16
	global_load_dwordx4 v[24:27], v[48:49], off
	v_pk_mul_f32 v[18:19], v[14:15], v[14:15]
	v_pk_mul_f32 v[44:45], v[42:43], v[42:43]
	v_add_f32_e32 v18, v18, v19
	v_add_f32_e32 v18, v44, v18
	v_pk_mul_f32 v[40:41], v[16:17], v[16:17]
	v_add_f32_e32 v18, v45, v18
	v_add_f32_e32 v18, v40, v18
	v_pk_mul_f32 v[38:39], v[36:37], v[36:37]
	v_add_f32_e32 v18, v41, v18
	v_add_f32_e32 v18, v38, v18
	v_add_f32_e32 v18, v39, v18
	s_nop 1
	v_add_f32_dpp v18, v18, v18 quad_perm:[1,0,3,2] row_mask:0xf bank_mask:0xf bound_ctrl:1
	s_nop 1
	v_add_f32_dpp v18, v18, v18 quad_perm:[2,3,0,1] row_mask:0xf bank_mask:0xf bound_ctrl:1
	s_nop 1
	v_add_f32_dpp v18, v18, v18 row_half_mirror row_mask:0xf bank_mask:0xf bound_ctrl:1
	s_nop 1
	v_add_f32_dpp v18, v18, v18 row_mirror row_mask:0xf bank_mask:0xf bound_ctrl:1
	v_fmamk_f32 v18, v18, 0x3c000000, v233
	v_rsq_f32_e32 v18, v18
	s_nop 0
	v_pk_mul_f32 v[14:15], v[14:15], v[18:19] op_sel_hi:[1,0]
	v_pk_mul_f32 v[16:17], v[16:17], v[18:19] op_sel_hi:[1,0]
	s_waitcnt vmcnt(0)
	v_pk_mul_f32 v[14:15], v[24:25], v[14:15]
	v_pk_mul_f32 v[24:25], v[42:43], v[18:19] op_sel_hi:[1,0]
	v_pk_mul_f32 v[18:19], v[36:37], v[18:19] op_sel_hi:[1,0]
	v_pk_mul_f32 v[16:17], v[20:21], v[16:17]
	v_pk_mul_f32 v[18:19], v[18:19], v[22:23]
	v_pk_mul_f32 v[24:25], v[26:27], v[24:25]
	v_pk_mul_f32 v[16:17], v[32:33], v[16:17]
	v_pk_mul_f32 v[18:19], v[34:35], v[18:19]
	v_pk_mul_f32 v[14:15], v[28:29], v[14:15]
	v_pk_mul_f32 v[24:25], v[30:31], v[24:25]
	v_cvt_pk_bf16_f32 v16, v16, v17
	v_cvt_pk_bf16_f32 v17, v18, v19
	v_lshlrev_b64 v[18:19], 12, v[52:53]
	v_cvt_pk_bf16_f32 v14, v14, v15
	v_cvt_pk_bf16_f32 v15, v24, v25
	v_lshl_add_u64 v[18:19], v[46:47], 0, v[18:19]
	global_store_dwordx4 v[18:19], v[14:17], off
	v_lshlrev_b32_e32 v20, 16, v12
	v_and_b32_e32 v12, 0xffff0000, v12
	v_lshlrev_b32_e32 v14, 16, v10
	v_and_b32_e32 v10, 0xffff0000, v10
	v_mul_f32_e32 v10, 0xbfb8aa3b, v10
	v_exp_f32_e32 v10, v10
	v_lshlrev_b32_e32 v15, 16, v11
	v_and_b32_e32 v11, 0xffff0000, v11
	v_lshlrev_b32_e32 v22, 16, v13
	v_add_f32_e32 v10, 1.0, v10
	v_rcp_f32_e32 v17, v10
	v_mul_f32_e32 v10, 0xbfb8aa3b, v15
	v_exp_f32_e32 v10, v10
	v_and_b32_e32 v13, 0xffff0000, v13
	v_mul_f32_e32 v14, 0xbfb8aa3b, v14
	v_exp_f32_e32 v14, v14
	v_add_f32_e32 v10, 1.0, v10
	v_rcp_f32_e32 v18, v10
	v_mul_f32_e32 v10, 0xbfb8aa3b, v11
	v_exp_f32_e32 v10, v10
	v_and_b32_e32 v11, 0xffff0000, v5
	v_add_f32_e32 v14, 1.0, v14
	v_rcp_f32_e32 v16, v14
	v_add_f32_e32 v10, 1.0, v10
	v_rcp_f32_e32 v19, v10
	v_mul_f32_e32 v10, 0xbfb8aa3b, v20
	v_exp_f32_e32 v10, v10
	v_lshlrev_b32_e32 v30, 16, v3
	v_and_b32_e32 v31, 0xffff0000, v3
	v_lshlrev_b32_e32 v34, 16, v2
	v_add_f32_e32 v10, 1.0, v10
	v_rcp_f32_e32 v20, v10
	v_mul_f32_e32 v10, 0xbfb8aa3b, v12
	v_exp_f32_e32 v10, v10
	v_lshlrev_b32_e32 v12, 16, v9
	v_and_b32_e32 v35, 0xffff0000, v2
	v_lshlrev_b32_e32 v2, 16, v6
	v_add_f32_e32 v10, 1.0, v10
	v_rcp_f32_e32 v21, v10
	v_mul_f32_e32 v10, 0xbfb8aa3b, v22
	v_exp_f32_e32 v10, v10
	v_and_b32_e32 v3, 0xffff0000, v6
	v_lshlrev_b32_e32 v32, 16, v7
	v_and_b32_e32 v33, 0xffff0000, v7
	v_add_f32_e32 v10, 1.0, v10
	v_rcp_f32_e32 v22, v10
	v_mul_f32_e32 v10, 0xbfb8aa3b, v13
	v_exp_f32_e32 v10, v10
	v_and_b32_e32 v13, 0xffff0000, v9
	v_pk_add_f32 v[2:3], v[34:35], v[2:3]
	v_pk_add_f32 v[30:31], v[30:31], v[32:33]
	v_add_f32_e32 v10, 1.0, v10
	v_rcp_f32_e32 v23, v10
	v_lshlrev_b32_e32 v10, 16, v5
	v_pk_add_f32 v[24:25], v[10:11], v[12:13]
	v_lshlrev_b32_e32 v10, 16, v4
	v_and_b32_e32 v11, 0xffff0000, v4
	v_lshlrev_b32_e32 v4, 16, v8
	v_and_b32_e32 v5, 0xffff0000, v8
	v_pk_add_f32 v[4:5], v[10:11], v[4:5]
	global_load_dwordx4 v[8:11], v[48:49], off offset:16
	global_load_dwordx4 v[12:15], v[48:49], off
	v_pk_mul_f32 v[6:7], v[2:3], v[2:3]
	v_pk_mul_f32 v[32:33], v[30:31], v[30:31]
	v_add_f32_e32 v6, v6, v7
	v_add_f32_e32 v6, v32, v6
	v_pk_mul_f32 v[28:29], v[4:5], v[4:5]
	v_add_f32_e32 v6, v33, v6
	v_add_f32_e32 v6, v28, v6
	v_pk_mul_f32 v[26:27], v[24:25], v[24:25]
	v_add_f32_e32 v6, v29, v6
	v_add_f32_e32 v6, v26, v6
	v_add_f32_e32 v6, v27, v6
	s_nop 1
	v_add_f32_dpp v6, v6, v6 quad_perm:[1,0,3,2] row_mask:0xf bank_mask:0xf bound_ctrl:1
	s_nop 1
	v_add_f32_dpp v6, v6, v6 quad_perm:[2,3,0,1] row_mask:0xf bank_mask:0xf bound_ctrl:1
	s_nop 1
	v_add_f32_dpp v6, v6, v6 row_half_mirror row_mask:0xf bank_mask:0xf bound_ctrl:1
	s_nop 1
	v_add_f32_dpp v6, v6, v6 row_mirror row_mask:0xf bank_mask:0xf bound_ctrl:1
	v_fmamk_f32 v6, v6, 0x3c000000, v233
	v_rsq_f32_e32 v6, v6
	s_nop 0
	v_pk_mul_f32 v[2:3], v[2:3], v[6:7] op_sel_hi:[1,0]
	v_pk_mul_f32 v[4:5], v[4:5], v[6:7] op_sel_hi:[1,0]
	s_waitcnt vmcnt(0)
	v_pk_mul_f32 v[2:3], v[12:13], v[2:3]
	v_pk_mul_f32 v[12:13], v[30:31], v[6:7] op_sel_hi:[1,0]
	v_pk_mul_f32 v[6:7], v[24:25], v[6:7] op_sel_hi:[1,0]
	v_pk_mul_f32 v[4:5], v[8:9], v[4:5]
	v_pk_mul_f32 v[6:7], v[6:7], v[10:11]
	v_pk_mul_f32 v[12:13], v[14:15], v[12:13]
	v_pk_mul_f32 v[4:5], v[20:21], v[4:5]
	v_pk_mul_f32 v[6:7], v[22:23], v[6:7]
	v_pk_mul_f32 v[2:3], v[16:17], v[2:3]
	v_pk_mul_f32 v[12:13], v[18:19], v[12:13]
	v_cvt_pk_bf16_f32 v4, v4, v5
	v_cvt_pk_bf16_f32 v5, v6, v7
	v_lshlrev_b64 v[6:7], 12, v[50:51]
	v_cvt_pk_bf16_f32 v2, v2, v3
	v_cvt_pk_bf16_f32 v3, v12, v13
	v_lshl_add_u64 v[6:7], v[46:47], 0, v[6:7]
	global_store_dwordx4 v[6:7], v[2:5], off
	s_cbranch_vccnz .LBB0_463
	s_branch .LBB0_403
